# P2 two queues (sample attention / prompt attention+conv): 128 workgroups pull SA first, 128 pull PA+conv first, each falls back to the other queue
# speedup vs baseline: 1.0282x; 1.0169x over previous
.LBB0_436:
	v_readlane_b32 s100, v248, 42
	s_mov_b32 s101, 0
	s_lshr_b32 s100, s100, 3
	s_and_b32 s100, s100, 7
	s_cmpk_lt_u32 s100, 4
	s_cselect_b32 s100, 1, 0
	s_load_dwordx4 s[28:31], s[52:53], 0x80
	s_waitcnt lgkmcnt(0)
	s_cmp_lt_i32 s30, 3
	s_cselect_b64 s[0:1], -1, 0
	s_and_b64 s[0:1], s[0:1], s[6:7]
	s_andn2_b64 vcc, exec, s[0:1]
	s_cbranch_vccnz .LBB0_610
	s_load_dwordx16 s[12:27], s[52:53], 0x0
	v_writelane_b32 v248, s0, 48
	v_mbcnt_lo_u32_b32 v3, -1, 0
	s_mov_b32 s11, 0x27000
	v_writelane_b32 v248, s1, 49
	s_waitcnt lgkmcnt(0)
	s_mov_b64 s[6:7], s[18:19]
	s_and_b32 s9, s7, 0xffff
	v_writelane_b32 v248, s33, 46
	s_add_u32 s0, s28, 0x2900000
	v_writelane_b32 v248, s0, 47
	s_addc_u32 s0, s29, 0
	v_writelane_b32 v248, s0, 44
	s_add_i32 s2, 0, 0x23200
	s_brev_b32 s10, -2
	s_mov_b32 s8, s18
	s_mov_b64 s[0:1], -1
	s_mov_b32 s21, 0
	v_mov_b32_e32 v2, 0
	v_writelane_b32 v248, s2, 38
	v_mov_b32_e32 v1, s2
	s_add_i32 s51, 0, 0x20000
	s_movk_i32 s33, 0x1000
	s_movk_i32 s50, 0x2000
	s_add_i32 s2, 0, 0x20800
	s_movk_i32 s19, 0x3000
	s_add_i32 s46, 0, 0x10000
	s_movk_i32 s6, 0x4000
	s_movk_i32 s17, 0x6000
	s_mov_b32 s31, 0x41000000
	s_movk_i32 s22, 0x5000
	s_movk_i32 s30, 0x7000
	v_mov_b32_e32 v204, 0x358637bd
	s_mov_b32 s18, 0xf800000
	v_mov_b32_e32 v205, 0x260
	v_mov_b32_e32 v196, 0xe0ad78ec
	v_mbcnt_hi_u32_b32 v206, -1, v3
	v_mov_b32_e32 v207, 3
	v_mov_b32_e32 v208, 2
	v_mov_b32_e32 v209, 1
	s_mov_b64 s[26:27], 0x100
	s_mov_b64 s[28:29], 0x1800
	s_mov_b64 s[34:35], 0x1900
	v_writelane_b32 v248, s2, 50
	s_branch .LBB0_440

.LBB0_445:
	s_load_dwordx4 s[4:7], s[52:53], 0x80
	v_mov_b32_e32 v4, 1
	s_waitcnt lgkmcnt(0)
	s_cmp_lg_u32 s101, 0
	s_cbranch_scc1 .Lq_second
	s_cmp_lg_u32 s100, 0
	s_cbranch_scc0 .Lq_p_other
	global_atomic_add v4, v2, v4, s[4:5] offset:256 sc0
	s_waitcnt vmcnt(0)
	v_readfirstlane_b32 s6, v4
	s_cmpk_lt_u32 s6, 0x180
	s_cbranch_scc0 .Lq_p_exh
	s_addk_i32 s6, 0x202
	s_branch .Lq_done
.Lq_p_other:
	global_atomic_add v4, v2, v4, s[4:5] offset:1024 sc0
	s_waitcnt vmcnt(0)
	v_readfirstlane_b32 s6, v4
	s_cmpk_lt_u32 s6, 0x202
	s_cbranch_scc0 .Lq_p_exh
	s_cmpk_lt_u32 s6, 0x180
	s_cbranch_scc0 .Lq_cva
	s_addk_i32 s6, 0x82
	s_branch .Lq_done
.Lq_cva:
	s_addk_i32 s6, 0xfe80
	s_branch .Lq_done
.Lq_p_exh:
	s_mov_b32 s101, 1
	v_mov_b32_e32 v4, 1
.Lq_second:
	s_cmp_lg_u32 s100, 0
	s_cbranch_scc1 .Lq_s_other
	global_atomic_add v4, v2, v4, s[4:5] offset:256 sc0
	s_waitcnt vmcnt(0)
	v_readfirstlane_b32 s6, v4
	s_cmpk_lt_u32 s6, 0x180
	s_cbranch_scc0 .Lq_none
	s_addk_i32 s6, 0x202
	s_branch .Lq_done

.Lq_none:
	s_movk_i32 s6, 0x382
